# plus: grid barrier: non-leader workgroups wait on the global generation word directly (one hand-off hop less per barrier)
# speedup vs baseline: 1.0100x; 1.0054x over previous
.LBB0_239:
	s_or_b64 exec, exec, s[10:11]
	v_cvt_f32_u32_e32 v4, v2
	s_waitcnt vmcnt(0)
	v_readfirstlane_b32 s8, v3
	v_sub_u32_e32 v3, 0, v2
	v_rcp_iflag_f32_e32 v4, v4
	v_add_u32_e32 v5, s8, v1
	v_mul_f32_e32 v4, 0x4f7ffffe, v4
	v_cvt_u32_f32_e32 v4, v4
	v_mul_lo_u32 v1, v3, v4
	v_mul_hi_u32 v1, v4, v1
	v_add_u32_e32 v1, v4, v1
	v_mul_hi_u32 v1, v5, v1
	v_mul_lo_u32 v3, v1, v2
	v_sub_u32_e32 v3, v5, v3
	v_add_u32_e32 v4, 1, v1
	v_cmp_ge_u32_e32 vcc, v3, v2
	s_nop 1
	v_cndmask_b32_e32 v1, v1, v4, vcc
	v_sub_u32_e32 v4, v3, v2
	v_cndmask_b32_e32 v3, v3, v4, vcc
	v_add_u32_e32 v4, 1, v1
	v_cmp_ge_u32_e32 vcc, v3, v2
	v_add_u32_e32 v3, 1, v5
	s_nop 0
	v_cndmask_b32_e32 v1, v1, v4, vcc
	v_mul_lo_u32 v4, v2, v1
	v_add_u32_e32 v2, v4, v2
	v_cmp_ne_u32_e32 vcc, v3, v2
	s_and_saveexec_b64 s[8:9], vcc
	s_xor_b64 s[8:9], exec, s[8:9]
	s_cbranch_execz .LBB0_253
	s_waitcnt lgkmcnt(0)
	s_add_u32 s14, s80, 0x551b600
	s_addc_u32 s15, s81, 0
	v_mov_b32_e32 v0, 0
	global_load_dword v0, v0, s[14:15] sc1
	s_waitcnt vmcnt(0)
	v_cmp_eq_u32_e32 vcc, v0, v1
	s_and_saveexec_b64 s[10:11], vcc
	s_cbranch_execz .LBB0_252
	s_add_u32 s12, s80, 0x5518300
	s_addc_u32 s13, s81, 0
	s_mov_b32 s26, 1
	s_mov_b64 s[16:17], 0
	v_mov_b32_e32 v0, 0
	s_branch .LBB0_243

.LBB0_300:
	s_or_b64 exec, exec, s[8:9]
	v_cvt_f32_u32_e32 v4, v2
	s_waitcnt vmcnt(0)
	v_readfirstlane_b32 s6, v3
	v_sub_u32_e32 v3, 0, v2
	v_rcp_iflag_f32_e32 v4, v4
	v_add_u32_e32 v5, s6, v1
	v_mul_f32_e32 v4, 0x4f7ffffe, v4
	v_cvt_u32_f32_e32 v4, v4
	v_mul_lo_u32 v1, v3, v4
	v_mul_hi_u32 v1, v4, v1
	v_add_u32_e32 v1, v4, v1
	v_mul_hi_u32 v1, v5, v1
	v_mul_lo_u32 v3, v1, v2
	v_sub_u32_e32 v3, v5, v3
	v_add_u32_e32 v4, 1, v1
	v_cmp_ge_u32_e32 vcc, v3, v2
	s_nop 1
	v_cndmask_b32_e32 v1, v1, v4, vcc
	v_sub_u32_e32 v4, v3, v2
	v_cndmask_b32_e32 v3, v3, v4, vcc
	v_add_u32_e32 v4, 1, v1
	v_cmp_ge_u32_e32 vcc, v3, v2
	v_add_u32_e32 v3, 1, v5
	s_nop 0
	v_cndmask_b32_e32 v1, v1, v4, vcc
	v_mul_lo_u32 v4, v2, v1
	v_add_u32_e32 v2, v4, v2
	v_cmp_ne_u32_e32 vcc, v3, v2
	s_and_saveexec_b64 s[6:7], vcc
	s_xor_b64 s[6:7], exec, s[6:7]
	s_cbranch_execz .LBB0_314
	s_waitcnt lgkmcnt(0)
	s_add_u32 s12, s80, 0x551b600
	s_addc_u32 s13, s81, 0
	v_mov_b32_e32 v0, 0
	global_load_dword v0, v0, s[12:13] sc1
	s_waitcnt vmcnt(0)
	v_cmp_eq_u32_e32 vcc, v0, v1
	s_and_saveexec_b64 s[8:9], vcc
	s_cbranch_execz .LBB0_313
	s_add_u32 s10, s80, 0x5518300
	s_addc_u32 s11, s81, 0
	s_mov_b32 s24, 1
	s_mov_b64 s[14:15], 0
	v_mov_b32_e32 v0, 0
	s_branch .LBB0_304

.LBB0_374:
	s_lshl_b32 s4, s33, 8
	s_add_u32 s4, s80, s4
	s_addc_u32 s5, s81, 0
	v_mov_b32_e32 v3, s4
	v_add_co_u32_e32 v4, vcc, 0x5519000, v3
	v_mov_b32_e32 v3, s5
	s_nop 0
	v_addc_co_u32_e32 v5, vcc, 0, v3, vcc
	flat_atomic_add v4, v[4:5], v248 offset:1280 sc0
	v_cvt_f32_u32_e32 v3, v2
	v_sub_u32_e32 v5, 0, v2
	s_add_u32 s27, s4, 0x5518100
	s_addc_u32 s26, s5, 0
	v_rcp_iflag_f32_e32 v3, v3
	s_nop 0
	v_mul_f32_e32 v3, 0x4f7ffffe, v3
	v_cvt_u32_f32_e32 v3, v3
	v_mul_lo_u32 v5, v5, v3
	v_mul_hi_u32 v5, v3, v5
	v_add_u32_e32 v3, v3, v5
	s_waitcnt vmcnt(0) lgkmcnt(0)
	v_mul_hi_u32 v3, v4, v3
	v_mul_lo_u32 v5, v3, v2
	v_sub_u32_e32 v5, v4, v5
	v_cmp_ge_u32_e32 vcc, v5, v2
	v_add_u32_e32 v6, 1, v3
	s_nop 0
	v_cndmask_b32_e32 v3, v3, v6, vcc
	v_sub_u32_e32 v6, v5, v2
	v_cndmask_b32_e32 v5, v5, v6, vcc
	v_cmp_ge_u32_e32 vcc, v5, v2
	v_add_u32_e32 v5, 1, v3
	v_add_u32_e32 v6, 1, v4
	v_cndmask_b32_e32 v3, v3, v5, vcc
	v_mad_u64_u32 v[4:5], s[4:5], v2, v3, v[2:3]
	v_cmp_ne_u32_e32 vcc, v6, v4
	s_and_saveexec_b64 s[4:5], vcc
	s_xor_b64 s[4:5], exec, s[4:5]
	s_cbranch_execz .LBB0_387
	s_add_u32 s8, s80, 0x551b600
	s_addc_u32 s9, s81, 0
	v_mov_b64_e32 v[4:5], s[8:9]
	flat_load_dword v0, v[4:5] sc1
	s_waitcnt vmcnt(0) lgkmcnt(0)
	v_cmp_eq_u32_e32 vcc, v0, v3
	s_and_saveexec_b64 s[6:7], vcc
	s_cbranch_execz .LBB0_386
	s_add_u32 s10, s80, 0x5518300
	s_addc_u32 s11, s81, 0
	s_mov_b32 s28, 1
	s_mov_b64 s[12:13], 0
	s_branch .LBB0_378

.LBB0_467:
	s_lshl_b32 s4, s53, 8
	s_add_u32 s4, s80, s4
	s_addc_u32 s5, s81, 0
	v_mov_b32_e32 v3, s4
	v_add_co_u32_e32 v4, vcc, 0x5519000, v3
	v_mov_b32_e32 v3, s5
	s_nop 0
	v_addc_co_u32_e32 v5, vcc, 0, v3, vcc
	flat_atomic_add v4, v[4:5], v248 offset:1280 sc0
	v_cvt_f32_u32_e32 v3, v2
	v_sub_u32_e32 v5, 0, v2
	s_add_u32 s27, s4, 0x5518100
	s_addc_u32 s26, s5, 0
	v_rcp_iflag_f32_e32 v3, v3
	s_nop 0
	v_mul_f32_e32 v3, 0x4f7ffffe, v3
	v_cvt_u32_f32_e32 v3, v3
	v_mul_lo_u32 v5, v5, v3
	v_mul_hi_u32 v5, v3, v5
	v_add_u32_e32 v3, v3, v5
	s_waitcnt vmcnt(0) lgkmcnt(0)
	v_mul_hi_u32 v3, v4, v3
	v_mul_lo_u32 v5, v3, v2
	v_sub_u32_e32 v5, v4, v5
	v_cmp_ge_u32_e32 vcc, v5, v2
	v_add_u32_e32 v6, 1, v3
	s_nop 0
	v_cndmask_b32_e32 v3, v3, v6, vcc
	v_sub_u32_e32 v6, v5, v2
	v_cndmask_b32_e32 v5, v5, v6, vcc
	v_cmp_ge_u32_e32 vcc, v5, v2
	v_add_u32_e32 v5, 1, v3
	v_add_u32_e32 v6, 1, v4
	v_cndmask_b32_e32 v3, v3, v5, vcc
	v_mad_u64_u32 v[4:5], s[4:5], v2, v3, v[2:3]
	v_cmp_ne_u32_e32 vcc, v6, v4
	s_and_saveexec_b64 s[4:5], vcc
	s_xor_b64 s[4:5], exec, s[4:5]
	v_readlane_b32 s68, v254, 63
	s_cbranch_execz .LBB0_480
	s_add_u32 s8, s80, 0x551b600
	s_addc_u32 s9, s81, 0
	v_mov_b64_e32 v[4:5], s[8:9]
	flat_load_dword v0, v[4:5] sc1
	s_waitcnt vmcnt(0) lgkmcnt(0)
	v_cmp_eq_u32_e32 vcc, v0, v3
	s_and_saveexec_b64 s[6:7], vcc
	s_cbranch_execz .LBB0_479
	s_add_u32 s10, s80, 0x5518300
	s_addc_u32 s11, s81, 0
	s_mov_b32 s28, 1
	s_mov_b64 s[12:13], 0
	s_branch .LBB0_471

.LBB0_676:
	s_lshl_b32 s0, s53, 8
	s_add_u32 s0, s80, s0
	s_addc_u32 s1, s81, 0
	v_mov_b32_e32 v3, s0
	v_add_co_u32_e32 v4, vcc, 0x5519000, v3
	v_mov_b32_e32 v3, s1
	s_nop 0
	v_addc_co_u32_e32 v5, vcc, 0, v3, vcc
	flat_atomic_add v4, v[4:5], v248 offset:1280 sc0
	v_cvt_f32_u32_e32 v3, v2
	v_sub_u32_e32 v5, 0, v2
	s_add_u32 s25, s0, 0x5518100
	s_addc_u32 s24, s1, 0
	v_rcp_iflag_f32_e32 v3, v3
	s_nop 0
	v_mul_f32_e32 v3, 0x4f7ffffe, v3
	v_cvt_u32_f32_e32 v3, v3
	v_mul_lo_u32 v5, v5, v3
	v_mul_hi_u32 v5, v3, v5
	v_add_u32_e32 v3, v3, v5
	s_waitcnt vmcnt(0) lgkmcnt(0)
	v_mul_hi_u32 v3, v4, v3
	v_mul_lo_u32 v5, v3, v2
	v_sub_u32_e32 v5, v4, v5
	v_cmp_ge_u32_e32 vcc, v5, v2
	v_add_u32_e32 v6, 1, v3
	s_nop 0
	v_cndmask_b32_e32 v3, v3, v6, vcc
	v_sub_u32_e32 v6, v5, v2
	v_cndmask_b32_e32 v5, v5, v6, vcc
	v_cmp_ge_u32_e32 vcc, v5, v2
	v_add_u32_e32 v5, 1, v3
	v_add_u32_e32 v6, 1, v4
	v_cndmask_b32_e32 v3, v3, v5, vcc
	v_mad_u64_u32 v[4:5], s[0:1], v2, v3, v[2:3]
	v_cmp_ne_u32_e32 vcc, v6, v4
	s_and_saveexec_b64 s[0:1], vcc
	s_xor_b64 s[0:1], exec, s[0:1]
	s_cbranch_execz .LBB0_689
	s_add_u32 s6, s80, 0x551b600
	s_addc_u32 s7, s81, 0
	v_mov_b64_e32 v[4:5], s[6:7]
	flat_load_dword v0, v[4:5] sc1
	s_waitcnt vmcnt(0) lgkmcnt(0)
	v_cmp_eq_u32_e32 vcc, v0, v3
	s_and_saveexec_b64 s[4:5], vcc
	s_cbranch_execz .LBB0_688
	s_add_u32 s8, s80, 0x5518300
	s_addc_u32 s9, s81, 0
	s_mov_b32 s26, 1
	s_mov_b64 s[10:11], 0
	s_branch .LBB0_680

.LBB0_813:
	s_lshl_b32 s0, s33, 8
	s_add_u32 s0, s80, s0
	s_addc_u32 s1, s81, 0
	v_mov_b32_e32 v3, s0
	v_add_co_u32_e32 v4, vcc, 0x5519000, v3
	v_mov_b32_e32 v3, s1
	s_nop 0
	v_addc_co_u32_e32 v5, vcc, 0, v3, vcc
	flat_atomic_add v4, v[4:5], v248 offset:1280 sc0
	v_cvt_f32_u32_e32 v3, v2
	v_sub_u32_e32 v5, 0, v2
	s_add_u32 s25, s0, 0x5518100
	s_addc_u32 s24, s1, 0
	v_rcp_iflag_f32_e32 v3, v3
	s_nop 0
	v_mul_f32_e32 v3, 0x4f7ffffe, v3
	v_cvt_u32_f32_e32 v3, v3
	v_mul_lo_u32 v5, v5, v3
	v_mul_hi_u32 v5, v3, v5
	v_add_u32_e32 v3, v3, v5
	s_waitcnt vmcnt(0) lgkmcnt(0)
	v_mul_hi_u32 v3, v4, v3
	v_mul_lo_u32 v5, v3, v2
	v_sub_u32_e32 v5, v4, v5
	v_cmp_ge_u32_e32 vcc, v5, v2
	v_add_u32_e32 v6, 1, v3
	s_nop 0
	v_cndmask_b32_e32 v3, v3, v6, vcc
	v_sub_u32_e32 v6, v5, v2
	v_cndmask_b32_e32 v5, v5, v6, vcc
	v_cmp_ge_u32_e32 vcc, v5, v2
	v_add_u32_e32 v5, 1, v3
	v_add_u32_e32 v6, 1, v4
	v_cndmask_b32_e32 v3, v3, v5, vcc
	v_mad_u64_u32 v[4:5], s[0:1], v2, v3, v[2:3]
	v_cmp_ne_u32_e32 vcc, v6, v4
	s_and_saveexec_b64 s[0:1], vcc
	s_xor_b64 s[0:1], exec, s[0:1]
	s_cbranch_execz .LBB0_826
	s_add_u32 s6, s80, 0x551b600
	s_addc_u32 s7, s81, 0
	v_mov_b64_e32 v[4:5], s[6:7]
	flat_load_dword v0, v[4:5] sc1
	s_waitcnt vmcnt(0) lgkmcnt(0)
	v_cmp_eq_u32_e32 vcc, v0, v3
	s_and_saveexec_b64 s[4:5], vcc
	s_cbranch_execz .LBB0_825
	s_add_u32 s8, s80, 0x5518300
	s_addc_u32 s9, s81, 0
	s_mov_b32 s26, 1
	s_mov_b64 s[10:11], 0
	s_branch .LBB0_817

.LBB0_1041:
	s_lshl_b32 s0, s33, 8
	s_add_u32 s0, s80, s0
	s_addc_u32 s1, s81, 0
	v_mov_b32_e32 v3, s0
	v_add_co_u32_e32 v4, vcc, 0x5519000, v3
	v_mov_b32_e32 v3, s1
	s_nop 0
	v_addc_co_u32_e32 v5, vcc, 0, v3, vcc
	flat_atomic_add v3, v[4:5], v248 offset:1280 sc0
	v_cvt_f32_u32_e32 v4, v2
	v_sub_u32_e32 v5, 0, v2
	s_add_u32 s25, s0, 0x5518100
	s_addc_u32 s24, s1, 0
	v_rcp_iflag_f32_e32 v4, v4
	s_waitcnt vmcnt(0) lgkmcnt(0)
	v_add_u32_e32 v6, 1, v3
	v_mul_f32_e32 v4, 0x4f7ffffe, v4
	v_cvt_u32_f32_e32 v4, v4
	v_mul_lo_u32 v5, v5, v4
	v_mul_hi_u32 v5, v4, v5
	v_add_u32_e32 v4, v4, v5
	v_mul_hi_u32 v4, v3, v4
	v_mul_lo_u32 v5, v4, v2
	v_sub_u32_e32 v3, v3, v5
	v_add_u32_e32 v7, 1, v4
	v_cmp_ge_u32_e32 vcc, v3, v2
	v_sub_u32_e32 v5, v3, v2
	s_nop 0
	v_cndmask_b32_e32 v4, v4, v7, vcc
	v_cndmask_b32_e32 v3, v3, v5, vcc
	v_add_u32_e32 v5, 1, v4
	v_cmp_ge_u32_e32 vcc, v3, v2
	s_nop 1
	v_cndmask_b32_e32 v3, v4, v5, vcc
	v_mad_u64_u32 v[4:5], s[0:1], v2, v3, v[2:3]
	v_cmp_ne_u32_e32 vcc, v6, v4
	s_and_saveexec_b64 s[0:1], vcc
	s_xor_b64 s[0:1], exec, s[0:1]
	s_cbranch_execz .LBB0_1054
	s_add_u32 s6, s80, 0x551b600
	s_addc_u32 s7, s81, 0
	v_mov_b64_e32 v[4:5], s[6:7]
	flat_load_dword v0, v[4:5] sc1
	s_waitcnt vmcnt(0) lgkmcnt(0)
	v_cmp_eq_u32_e32 vcc, v0, v3
	s_and_saveexec_b64 s[4:5], vcc
	s_cbranch_execz .LBB0_1053
	s_add_u32 s8, s80, 0x5518300
	s_addc_u32 s9, s81, 0
	s_mov_b32 s26, 1
	s_mov_b64 s[10:11], 0
	s_branch .LBB0_1045
